# HGRN raw staging ring re-pitched (chunk 1088 -> 1056 bytes) so quarter-wave raw reads hit disjoint LDS banks
# baseline (speedup 1.0000x reference)
; #define LAS __attribute__((address_space(3)))
; __device__ __forceinline__ int otid() { int t = threadIdx.x; asm volatile("" : "+v"(t)); return t; }
; template <bool DRY> __device__ __forceinline__ void hgrn_unit(LAS unsigned char* lds, int b, int h, int vs, int layer, bf16_t* Pm, const float* lbraw) {
;     using namespace hg;
;     const int tid = otid(), lane = tid & 63; const int wid = __builtin_amdgcn_readfirstlane(tid >> 6);
;     const size_t tok0 = (size_t)b * SEQ;
;     const int kl = lane & 15, tq = lane >> 4, kch = 16 * wid + kl;
;     (void)layer; (void)lbraw;
;     const bf16_t* qsrc = Pm + (tok0 + 4 * tq) * PW + PC_HQ + h * 128 + (kch & ~1);
;     const bf16_t* fsrc = Pm + (tok0 + 4 * tq) * PW + PC_HF + h * 128 + (kch & ~1);
;     const bool isv = tid < 128; const int vv = tid & 31, vtq = (tid >> 5) & 3;
;     const bf16_t* vsrc = Pm + (tok0 + 4 * vtq) * PW + PC_HI + h * 128 + vs * 32 + (vv & ~1);
;     constexpr int NSTEP = SEQ / 16;
;     for (int i = tid; i < SB / 4; i += NTHREADS) ((LAS unsigned*)(lds + OFF_S + SB))[i] = 0u;
;     Raw ra, rb;
;     load_raw(ra, qsrc, fsrc, vsrc, 0, isv);
;     prep(ra, lds, lane, kch, tq, isv, vv, vtq);
;     load_raw(ra, qsrc, fsrc, vsrc, 1, isv); load_raw(rb, qsrc, fsrc, vsrc, 2, isv);
;     f32x16 sacc = {};
;     const int c16 = lane & 15, kq = lane >> 4, r32 = lane & 31, hh = lane >> 5;
;     __syncthreads();
.LBB0_615:
	s_or_b64 exec, exec, s[6:7]
	s_ashr_i32 s6, s22, 4
	s_ashr_i32 s7, s6, 31
	v_bfe_u32 v9, v3, 4, 2
	s_lshl_b64 s[14:15], s[6:7], 11
	v_lshlrev_b32_e32 v8, 2, v9
	v_or_b32_e32 v0, s14, v8
	v_mov_b64_e32 v[4:5], s[4:5]
	v_bfe_u32 v12, v3, 5, 2
	s_ashr_i32 s28, s10, 6
	s_mov_b32 s65, s28
	v_mad_u64_u32 v[0:1], s[6:7], v0, s24, v[4:5]
	s_lshl_b32 s10, s22, 5
	v_lshl_or_b32 v6, v12, 2, s14
	s_and_b32 s6, s10, 0x180
	v_mad_u64_u32 v[4:5], s[8:9], v6, s24, v[4:5]
	v_and_b32_e32 v7, 15, v3
	s_lshl_b32 s34, s28, 4
	v_mad_i32_i24 v1, s15, v240, v1
	s_lshl_b32 s6, s6, 1
	s_mov_b32 s7, s29
	v_mad_i32_i24 v5, s15, v240, v5
	v_lshl_add_u64 v[0:1], v[0:1], 0, s[6:7]
	v_bitop3_b32 v10, s34, -2, v7 bitop3:0xc8
	v_lshl_add_u64 v[4:5], v[4:5], 0, s[6:7]
	s_and_b32 s7, s10, 0x60
	v_ashrrev_i32_e32 v11, 31, v10
	s_lshl_b32 s8, s7, 1
	s_mul_i32 s41, s14, 0x1d40
	s_add_u32 s38, s4, s41
	s_addc_u32 s39, s5, 0
	s_add_u32 s38, s38, s6
	s_addc_u32 s39, s39, 0
	s_add_u32 s38, s38, 0xd00
	s_addc_u32 s39, s39, 0
	s_mov_b32 s9, s29
	v_and_b32_e32 v6, 30, v3
	v_lshl_add_u64 v[0:1], v[10:11], 1, v[0:1]
	v_lshl_add_u64 v[4:5], v[4:5], 0, s[8:9]
	v_lshlrev_b32_e32 v10, 1, v6
	v_mov_b32_e32 v11, v2
	s_movk_i32 s7, 0x1000
	v_lshl_add_u64 v[4:5], v[4:5], 0, v[10:11]
	v_add_co_u32_e32 v10, vcc, s7, v0
	v_cmp_eq_u32_e64 s[50:51], 3, v9
	s_nop 0
	v_addc_co_u32_e32 v11, vcc, 0, v1, vcc
	v_add_co_u32_e32 v14, vcc, s7, v4
	s_movk_i32 s7, 0x2000
	s_nop 0
	v_addc_co_u32_e32 v15, vcc, 0, v5, vcc
	v_add_co_u32_e32 v16, vcc, s7, v0
	s_movk_i32 s7, 0x3000
	s_nop 0
	v_addc_co_u32_e32 v17, vcc, 0, v1, vcc
	v_add_co_u32_e32 v18, vcc, s7, v4
	s_movk_i32 s7, 0x4000
	s_nop 0
	v_addc_co_u32_e32 v19, vcc, 0, v5, vcc
	v_add_co_u32_e32 v20, vcc, s7, v0
	s_nop 1
	v_addc_co_u32_e32 v21, vcc, 0, v1, vcc
	s_nop 0
	s_nop 0
	s_nop 0
	s_nop 0
	v_add_co_u32_e32 v10, vcc, s7, v4
	s_movk_i32 s7, 0x6000
	s_nop 0
	v_addc_co_u32_e32 v11, vcc, 0, v5, vcc
	v_add_co_u32_e32 v10, vcc, s7, v0
	s_nop 1
	v_addc_co_u32_e32 v11, vcc, 0, v1, vcc
	v_add_co_u32_e32 v18, vcc, s7, v4
	s_movk_i32 s7, 0x440
	s_nop 0
	v_addc_co_u32_e32 v19, vcc, 0, v5, vcc
	s_nop 0
	v_and_b32_e32 v19, 1, v3
	v_cmp_eq_u32_e64 s[44:45], 0, v19
	v_and_b32_e32 v11, 63, v3
	v_cmp_gt_u32_e64 s[46:47], 16, v11
	v_cmp_lt_u32_e64 s[48:49], 31, v11
	v_or_b32_e32 v10, s34, v7
	v_lshl_add_u32 v36, v10, 1, 0
	v_mad_u32_u24 v42, v9, s7, v36
	v_bfe_u32 v140, v234, 4, 2
	v_mul_u32_u24_e32 v136, 0x420, v140
	v_lshrrev_b32_e32 v140, 6, v234
	v_and_b32_e32 v141, 15, v234
	v_lshl_or_b32 v140, v140, 4, v141
	v_lshrrev_b32_e32 v140, 1, v140
	v_lshl_add_u32 v136, v140, 2, v136
	v_add_u32_e32 v136, 0xd400, v136
	v_bfe_i32 v145, v234, 4, 1
	v_and_b32_e32 v151, 1, v234
	v_mov_b32_e32 v152, 0x2020000
	v_mul_lo_u32 v151, v151, v152
	v_add_u32_e32 v151, 0x1000c0c, v151
	v_and_b32_e32 v186, 1, v234
	v_mov_b32_e32 v187, 0x403fbfc
	v_mul_lo_u32 v154, v186, v187
	v_add_u32_e32 v154, 0x1000504, v154
	v_add_u32_e32 v155, 0x2020202, v154
	v_mul_u32_u24_e32 v187, 0x220, v186
	v_add_u32_e32 v186, 0x3800, v187
	v_and_b32_e32 v144, 1, v234
	v_lshl_add_u32 v144, v144, 1, v136
	v_bfe_u32 v140, v234, 5, 2
	v_and_b32_e32 v141, 31, v234
	v_lshrrev_b32_e32 v141, 1, v141
	v_lshlrev_b32_e32 v141, 2, v141
	v_lshl_add_u32 v137, v140, 8, v141
	v_add_u32_e32 v137, 0xf500, v137
	v_and_b32_e32 v140, 63, v234
	v_lshrrev_b32_e32 v141, 4, v140
	v_lshrrev_b32_e32 v142, 6, v234
	v_and_b32_e32 v143, 3, v142
	v_lshl_add_u32 v141, v143, 2, v141
	v_mul_u32_u24_e32 v138, 0x1d40, v141
	v_and_b32_e32 v141, 15, v140
	v_lshl_add_u32 v138, v141, 4, v138
	v_lshrrev_b32_e32 v142, 2, v142
	v_lshl_add_u32 v138, v142, 10, v138
	v_lshrrev_b32_e32 v141, 2, v140
	v_mul_u32_u24_e32 v139, 0x1d40, v141
	v_and_b32_e32 v141, 3, v140
	v_lshl_add_u32 v139, v141, 4, v139
	v_add_u32_e32 v139, 0x800, v139
	v_add_u32_e32 v139, s8, v139
	s_mul_i32 s64, s65, 0x420
	s_add_i32 s64, s64, 0xd400
	s_mov_b64 s[42:43], s[38:39]
	s_cmp_lg_u32 s65, 7
	s_cbranch_scc1 .Lhg_pro_nov
	s_add_i32 m0, s64, 0
	s_nop 0
	global_load_lds_dwordx4 v138, s[42:43]
	s_mov_b32 m0, 0xf500
	s_nop 0
	global_load_lds_dwordx4 v139, s[42:43]
	s_add_u32 s42, s42, 0x1d400
	s_addc_u32 s43, s43, 0
	s_add_i32 m0, s64, 9792
	s_nop 0
	global_load_lds_dwordx4 v138, s[42:43]
	s_mov_b32 m0, 0x11b40
	s_nop 0
	global_load_lds_dwordx4 v139, s[42:43]
	s_add_u32 s42, s42, 0x1d400
	s_addc_u32 s43, s43, 0
	s_add_i32 m0, s64, 19584
	s_nop 0
	global_load_lds_dwordx4 v138, s[42:43]
	s_mov_b32 m0, 0x14180
	s_nop 0
	global_load_lds_dwordx4 v139, s[42:43]
	s_add_u32 s42, s42, 0x1d400
	s_addc_u32 s43, s43, 0
	s_add_i32 m0, s64, 29376
	s_nop 0
	global_load_lds_dwordx4 v138, s[42:43]
	s_mov_b32 m0, 0x167c0
	s_nop 0
	global_load_lds_dwordx4 v139, s[42:43]
	s_waitcnt vmcnt(4)
	s_branch .Lhg_pro_done

; #define LAS __attribute__((address_space(3)))
; __device__ __forceinline__ unsigned cvtpk(float lo, float hi) { f32x2_t v = {lo, hi}; bf16x2_t b = __builtin_convertvector(v, bf16x2_t); return __builtin_bit_cast(unsigned, b); }
; __device__ __forceinline__ void prep(const Raw& Rin, LAS unsigned char* buf, int lane, int kch, int tq, bool isv, int vv, int vtq) {
;     Raw R = Rin; const bool kodd = kch & 1, vodd = vv & 1;
; #pragma unroll
;     for (int i = 0; i < 4; ++i) { asm volatile("" : "+v"(R.q[i])); asm volatile("" : "+v"(R.f[i])); asm volatile("" : "+v"(R.v[i])); }
;     float qv[4], kk[4], c[4]; float run = 0.f;
; #pragma unroll
;     for (int i = 0; i < 4; ++i) {
;         qv[i] = __uint_as_float(kodd ? (R.q[i] & 0xffff0000u) : (R.q[i] << 16));
;         const float l2 = __uint_as_float(kodd ? (R.f[i] & 0xffff0000u) : (R.f[i] << 16));
;         kk[i] = 1.f - __builtin_amdgcn_exp2f(l2);
;         run += l2; c[i] = run;
;     }
;     const float p1 = __shfl(run, (lane - 16) & 63), p2 = __shfl(run, (lane - 32) & 63), p3 = __shfl(run, (lane - 48) & 63);
;     const float off = (tq >= 1 ? p1 : 0.f) + (tq >= 2 ? p2 : 0.f) + (tq >= 3 ? p3 : 0.f);
;     const float btot = __shfl(off + run, 48 + (lane & 15));
;     unsigned short kf[4];
; #pragma unroll
;     for (int i = 0; i < 4; ++i) {
;         const float bt = off + c[i];
;         const float qf = qv[i] * __builtin_amdgcn_exp2f(bt), kfv = kk[i] * __builtin_amdgcn_exp2f(-bt);
;         const unsigned pk = cvtpk(qf, kfv);
;         *(LAS unsigned short*)(buf + OFF_QF + (4 * tq + i) * STR + kch * 2) = (unsigned short)(pk & 0xffffu);
;         kf[i] = (unsigned short)(pk >> 16);
;         *(LAS unsigned short*)(buf + OFF_KF + (4 * tq + i) * STR + kch * 2) = kf[i];
;     }
;     *(LAS u32x2*)(buf + OFF_KFT + kch * 32 + tq * 8) = (u32x2){(unsigned)kf[0] | ((unsigned)kf[1] << 16), (unsigned)kf[2] | ((unsigned)kf[3] << 16)};
;     if (tq == 0) *(LAS float*)(buf + OFF_D + kch * 4) = __builtin_amdgcn_exp2f(btot);
;     if (isv) { unsigned v0 = vodd ? R.v[0] >> 16 : R.v[0] & 0xffffu, v1 = vodd ? R.v[1] >> 16 : R.v[1] & 0xffffu, v2 = vodd ? R.v[2] >> 16 : R.v[2] & 0xffffu, v3 = vodd ? R.v[3] >> 16 : R.v[3] & 0xffffu;
;         *(LAS u32x2*)(buf + OFF_VT + vv * 32 + vtq * 8) = (u32x2){v0 | (v1 << 16), v2 | (v3 << 16)}; }
; }
.Lhg_pro_done:
	s_barrier
	ds_read_b32 v6, v136
	ds_read_b32 v15, v136 offset:256
	ds_read_b32 v25, v136 offset:512
	ds_read_b32 v26, v136 offset:768
	ds_read_b32 v22, v136 offset:4224
	ds_read_b32 v16, v136 offset:4480
	ds_read_b32 v21, v136 offset:4736
	ds_read_b32 v29, v136 offset:4992
	ds_read_b32 v13, v137
	ds_read_b32 v14, v137 offset:64
	ds_read_b32 v17, v137 offset:128
	ds_read_b32 v18, v137 offset:192
	s_waitcnt lgkmcnt(0)
	s_nop 0
	v_and_b32_e32 v20, 0xffff0000, v6
	v_lshlrev_b32_e32 v6, 16, v6
	v_cndmask_b32_e64 v20, v20, v6, s[44:45]
	v_and_b32_e32 v6, 0xffff0000, v22
	v_lshlrev_b32_e32 v19, 16, v22
	v_cndmask_b32_e64 v6, v6, v19, s[44:45]
	v_exp_f32_e32 v19, v6
	v_add_f32_e32 v6, 0, v6
	v_sub_f32_e32 v23, 1.0, v19
	v_and_b32_e32 v19, 0xffff0000, v16
	v_lshlrev_b32_e32 v16, 16, v16
	v_cndmask_b32_e64 v16, v19, v16, s[44:45]
	v_exp_f32_e32 v19, v16
	v_and_b32_e32 v22, 0xffff0000, v15
	v_lshlrev_b32_e32 v15, 16, v15
	v_cndmask_b32_e64 v24, v22, v15, s[44:45]
	v_sub_f32_e32 v27, 1.0, v19
	v_add_f32_e32 v15, v6, v16
	v_and_b32_e32 v16, 0xffff0000, v21
	v_lshlrev_b32_e32 v19, 16, v21
	v_cndmask_b32_e64 v16, v16, v19, s[44:45]
	v_exp_f32_e32 v19, v16
	v_and_b32_e32 v21, 0xffff0000, v25
	v_lshlrev_b32_e32 v22, 16, v25
	v_cndmask_b32_e64 v28, v21, v22, s[44:45]
	v_sub_f32_e32 v31, 1.0, v19
	v_add_f32_e32 v19, v15, v16
	v_and_b32_e32 v16, 0xffff0000, v29
	v_lshlrev_b32_e32 v21, 16, v29
	v_cndmask_b32_e64 v16, v16, v21, s[44:45]
	v_exp_f32_e32 v21, v16
	v_and_b32_e32 v22, 0xffff0000, v26
	v_lshlrev_b32_e32 v25, 16, v26
	v_cndmask_b32_e64 v38, v22, v25, s[44:45]
	v_sub_f32_e32 v41, 1.0, v21
	v_add_u32_e32 v21, 48, v3
	v_or_b32_e32 v22, v239, v11
	v_and_or_b32 v21, v21, 63, v239
	v_lshlrev_b32_e32 v25, 2, v22
	v_add_u32_e32 v26, 16, v3
	v_add_f32_e32 v16, v19, v16
	v_lshlrev_b32_e32 v32, 2, v21
	v_xor_b32_e32 v33, 0x80, v25
	v_and_or_b32 v26, v26, 63, v239
	ds_bpermute_b32 v21, v32, v16
	ds_bpermute_b32 v22, v33, v16
	v_lshlrev_b32_e32 v34, 2, v26
	ds_bpermute_b32 v26, v34, v16
	v_or_b32_e32 v35, 0xc0, v25
	s_waitcnt lgkmcnt(2)
	v_cndmask_b32_e64 v21, v21, 0, s[46:47]
	s_waitcnt lgkmcnt(1)
	v_cndmask_b32_e64 v22, 0, v22, s[48:49]
	v_add_f32_e32 v21, v21, v22
	s_waitcnt lgkmcnt(0)
	v_cndmask_b32_e64 v22, 0, v26, s[50:51]
	v_add_f32_e32 v29, v21, v22
	v_add_f32_e32 v6, v6, v29
	v_exp_f32_e32 v22, v6
	v_exp_f32_e64 v21, -v6
	v_add_f32_e32 v15, v15, v29
	v_exp_f32_e32 v26, v15
	v_exp_f32_e64 v25, -v15
	v_add_f32_e32 v37, v16, v29
	v_add_f32_e32 v19, v19, v29
	v_pk_mul_f32 v[20:21], v[22:23], v[20:21]
	v_exp_f32_e32 v30, v19
	v_exp_f32_e64 v29, -v19
	v_exp_f32_e32 v40, v37
	v_exp_f32_e64 v39, -v37
	v_cvt_pk_bf16_f32 v6, v20, v21
	v_lshrrev_b32_e32 v15, 16, v6
	v_pk_mul_f32 v[20:21], v[26:27], v[24:25]
	ds_write_b16 v42, v15 offset:4352
	v_cvt_pk_bf16_f32 v15, v20, v21
	v_lshrrev_b32_e32 v19, 16, v15
	v_pk_mul_f32 v[20:21], v[30:31], v[28:29]
	v_pk_mul_f32 v[22:23], v[40:41], v[38:39]
	ds_bpermute_b32 v16, v35, v37
	ds_write_b16 v42, v6
	ds_write_b16 v42, v19 offset:4624
	v_cvt_pk_bf16_f32 v19, v20, v21
	v_perm_b32 v20, v15, v6, s17
	v_cvt_pk_bf16_f32 v6, v22, v23
	ds_write_b16 v42, v15 offset:272
	v_lshrrev_b32_e32 v15, 16, v6
	v_lshrrev_b32_e32 v21, 16, v19
	ds_write_b16 v42, v15 offset:5168
	v_mul_lo_u32 v15, v10, 30
	ds_write_b16 v42, v21 offset:4896
	ds_write_b16 v42, v6 offset:816
	v_perm_b32 v21, v6, v19, s17
	v_add_u32_e32 v6, v36, v15
	v_lshlrev_b32_e32 v37, 3, v9
	v_add_u32_e32 v38, v6, v37
	ds_write_b16 v42, v19 offset:544
	ds_write_b64 v38, v[20:21] offset:8704
	s_and_saveexec_b64 s[10:11], s[46:47]
	s_cbranch_execz .LBB0_617
	s_waitcnt lgkmcnt(8)
	v_exp_f32_e32 v16, v16
	s_movk_i32 s7, 0xffe4
	v_mad_u64_u32 v[20:21], s[12:13], v10, s7, v[6:7]
	ds_write_b32 v20, v16 offset:13824

; #define LAS __attribute__((address_space(3)))
; __device__ __forceinline__ unsigned cvtpk(float lo, float hi) { f32x2_t v = {lo, hi}; bf16x2_t b = __builtin_convertvector(v, bf16x2_t); return __builtin_bit_cast(unsigned, b); }
; __device__ __forceinline__ void prep(const Raw& Rin, LAS unsigned char* buf, int lane, int kch, int tq, bool isv, int vv, int vtq) {
;     Raw R = Rin; const bool kodd = kch & 1, vodd = vv & 1;
; #pragma unroll
;     for (int i = 0; i < 4; ++i) { asm volatile("" : "+v"(R.q[i])); asm volatile("" : "+v"(R.f[i])); asm volatile("" : "+v"(R.v[i])); }
;     float qv[4], kk[4], c[4]; float run = 0.f;
; #pragma unroll
;     for (int i = 0; i < 4; ++i) {
;         qv[i] = __uint_as_float(kodd ? (R.q[i] & 0xffff0000u) : (R.q[i] << 16));
;         const float l2 = __uint_as_float(kodd ? (R.f[i] & 0xffff0000u) : (R.f[i] << 16));
;         kk[i] = 1.f - __builtin_amdgcn_exp2f(l2);
;         run += l2; c[i] = run;
;     }
;     const float p1 = __shfl(run, (lane - 16) & 63), p2 = __shfl(run, (lane - 32) & 63), p3 = __shfl(run, (lane - 48) & 63);
;     const float off = (tq >= 1 ? p1 : 0.f) + (tq >= 2 ? p2 : 0.f) + (tq >= 3 ? p3 : 0.f);
;     const float btot = __shfl(off + run, 48 + (lane & 15));
;     unsigned short kf[4];
; #pragma unroll
;     for (int i = 0; i < 4; ++i) {
;         const float bt = off + c[i];
;         const float qf = qv[i] * __builtin_amdgcn_exp2f(bt), kfv = kk[i] * __builtin_amdgcn_exp2f(-bt);
;         const unsigned pk = cvtpk(qf, kfv);
;         *(LAS unsigned short*)(buf + OFF_QF + (4 * tq + i) * STR + kch * 2) = (unsigned short)(pk & 0xffffu);
;         kf[i] = (unsigned short)(pk >> 16);
;         *(LAS unsigned short*)(buf + OFF_KF + (4 * tq + i) * STR + kch * 2) = kf[i];
;     }
;     *(LAS u32x2*)(buf + OFF_KFT + kch * 32 + tq * 8) = (u32x2){(unsigned)kf[0] | ((unsigned)kf[1] << 16), (unsigned)kf[2] | ((unsigned)kf[3] << 16)};
;     if (tq == 0) *(LAS float*)(buf + OFF_D + kch * 4) = __builtin_amdgcn_exp2f(btot);
.LBB0_625:
	s_add_i32 s41, s7, 4
	s_min_u32 s41, s41, 0x7f
	s_mul_i32 s41, s41, 0x1d400
	s_add_u32 s42, s38, s41
	s_addc_u32 s43, s39, 0
	s_add_i32 s41, s7, 0
	s_and_b32 s41, s41, 3
	s_mul_i32 s41, s41, 9792
	s_add_i32 m0, s41, s64
	s_nop 0
	global_load_lds_dwordx4 v138, s[42:43]
	s_cmp_lg_u32 s65, 7
	s_cbranch_scc1 .Lhg_nov_a
	s_add_i32 m0, s41, 0xf500
	s_nop 0
	global_load_lds_dwordx4 v139, s[42:43]
.Lhg_nov_a:
	s_add_i32 s41, s7, 1
	s_and_b32 s41, s41, 3
	s_mul_i32 s41, s41, 9792
	v_add_u32_e32 v140, s41, v136
	v_add_u32_e32 v141, s41, v137
	v_add_u32_e32 v153, 0x1080, v140
	ds_read2_b32 v[156:157], v153 offset1:64
	ds_read2_b32 v[158:159], v153 offset0:128 offset1:192
	ds_read2_b32 v[160:161], v140 offset1:64
	ds_read2_b32 v[162:163], v140 offset0:128 offset1:192
	ds_read2_b32 v[40:41], v141 offset1:16
	ds_read2_b32 v[164:165], v141 offset0:32 offset1:48
	s_waitcnt lgkmcnt(4)
	v_perm_b32 v0, v156, v156, v151
	v_perm_b32 v1, v157, v157, v151
	v_perm_b32 v3, v158, v158, v151
	v_perm_b32 v56, v159, v159, v151
	v_exp_f32_e32 v81, v0
	v_exp_f32_e32 v83, v1
	v_exp_f32_e32 v87, v3
	v_exp_f32_e32 v54, v56
	v_add_f32_e32 v1, v0, v1
	v_add_f32_e32 v3, v1, v3
	v_add_f32_e32 v63, v3, v56
	v_mov_b32_e32 v146, v63
	v_mov_b32_e32 v147, v63
	v_sub_f32_e32 v81, 1.0, v81
	v_sub_f32_e32 v83, 1.0, v83
	v_permlane16_swap_b32_e32 v146, v147
	v_sub_f32_e32 v87, 1.0, v87
	v_add_f32_e32 v148, v146, v147
	v_mov_b32_e32 v149, v148
	v_and_b32_e32 v150, v146, v145
	s_nop 0
	v_permlane32_swap_b32_e32 v148, v149
	v_cndmask_b32_e64 v52, 0, v148, s[48:49]
	v_add_f32_e32 v52, v52, v150
	s_waitcnt lgkmcnt(0)
	v_perm_b32 v78, v160, v160, v151
	v_perm_b32 v62, v161, v161, v151
	v_perm_b32 v84, v162, v162, v151
	v_perm_b32 v88, v163, v163, v151
	v_add_f32_e32 v0, v0, v52
	v_exp_f32_e32 v80, v0
	v_exp_f32_e64 v79, -v0
	v_add_f32_e32 v1, v1, v52
	v_sub_f32_e32 v91, 1.0, v54
	v_add_f32_e32 v54, v63, v52
	v_exp_f32_e32 v82, v1
	v_exp_f32_e64 v63, -v1
	v_add_f32_e32 v3, v3, v52
	v_pk_mul_f32 v[78:79], v[80:81], v[78:79]
	v_exp_f32_e32 v86, v3
	v_exp_f32_e64 v85, -v3
	v_cvt_pk_bf16_f32 v170, v78, v79
	v_exp_f32_e32 v90, v54
	v_exp_f32_e64 v89, -v54
	v_add_u32_e32 v184, v26, v43
	v_pk_mul_f32 v[62:63], v[82:83], v[62:63]
	v_add_f32_e32 v0, v148, v149
	v_cvt_pk_bf16_f32 v171, v62, v63
	v_pk_mul_f32 v[62:63], v[86:87], v[84:85]
	v_and_b32_e32 v184, -4, v184
	v_cvt_pk_bf16_f32 v172, v62, v63
	v_pk_mul_f32 v[78:79], v[90:91], v[88:89]
	v_add_u32_e32 v184, v184, v186
	v_cvt_pk_bf16_f32 v173, v78, v79
	v_perm_b32 v62, v171, v170, s17
	v_perm_b32 v63, v173, v172, s17
	v_cndmask_b32_e64 v174, v170, v172, s[44:45]
	v_cndmask_b32_e64 v175, v171, v173, s[44:45]
	v_cndmask_b32_e64 v176, v172, v170, s[44:45]
	v_cndmask_b32_e64 v177, v173, v171, s[44:45]
	v_add_u32_e32 v185, 0x1100, v184
	v_mov_b32_dpp v178, v174 quad_perm:[1,0,3,2] row_mask:0xf bank_mask:0xf
	v_mov_b32_dpp v179, v175 quad_perm:[1,0,3,2] row_mask:0xf bank_mask:0xf
	v_add_u32_e32 v1, v27, v37
	v_perm_b32 v180, v176, v178, v154
	v_perm_b32 v181, v177, v179, v154
	v_perm_b32 v182, v176, v178, v155
	v_perm_b32 v183, v177, v179, v155
	ds_write2_b32 v184, v180, v181 offset1:68
	ds_write2_b32 v185, v182, v183 offset1:68
	ds_write_b64 v1, v[62:63] offset:23040
	s_and_saveexec_b64 s[14:15], s[46:47]
	s_cbranch_execz .LBB0_627
	s_waitcnt lgkmcnt(9)
	v_exp_f32_e32 v0, v0
	v_add_u32_e32 v1, v27, v45
	ds_write_b32 v1, v0 offset:28160

; #define LAS __attribute__((address_space(3)))
; __device__ __forceinline__ unsigned cvtpk(float lo, float hi) { f32x2_t v = {lo, hi}; bf16x2_t b = __builtin_convertvector(v, bf16x2_t); return __builtin_bit_cast(unsigned, b); }
; __device__ __forceinline__ void prep(const Raw& Rin, LAS unsigned char* buf, int lane, int kch, int tq, bool isv, int vv, int vtq) {
;     Raw R = Rin; const bool kodd = kch & 1, vodd = vv & 1;
; #pragma unroll
;     for (int i = 0; i < 4; ++i) { asm volatile("" : "+v"(R.q[i])); asm volatile("" : "+v"(R.f[i])); asm volatile("" : "+v"(R.v[i])); }
;     float qv[4], kk[4], c[4]; float run = 0.f;
; #pragma unroll
;     for (int i = 0; i < 4; ++i) {
;         qv[i] = __uint_as_float(kodd ? (R.q[i] & 0xffff0000u) : (R.q[i] << 16));
;         const float l2 = __uint_as_float(kodd ? (R.f[i] & 0xffff0000u) : (R.f[i] << 16));
;         kk[i] = 1.f - __builtin_amdgcn_exp2f(l2);
;         run += l2; c[i] = run;
;     }
;     const float p1 = __shfl(run, (lane - 16) & 63), p2 = __shfl(run, (lane - 32) & 63), p3 = __shfl(run, (lane - 48) & 63);
;     const float off = (tq >= 1 ? p1 : 0.f) + (tq >= 2 ? p2 : 0.f) + (tq >= 3 ? p3 : 0.f);
;     const float btot = __shfl(off + run, 48 + (lane & 15));
;     unsigned short kf[4];
; #pragma unroll
;     for (int i = 0; i < 4; ++i) {
;         const float bt = off + c[i];
;         const float qf = qv[i] * __builtin_amdgcn_exp2f(bt), kfv = kk[i] * __builtin_amdgcn_exp2f(-bt);
;         const unsigned pk = cvtpk(qf, kfv);
;         *(LAS unsigned short*)(buf + OFF_QF + (4 * tq + i) * STR + kch * 2) = (unsigned short)(pk & 0xffffu);
;         kf[i] = (unsigned short)(pk >> 16);
;         *(LAS unsigned short*)(buf + OFF_KF + (4 * tq + i) * STR + kch * 2) = kf[i];
;     }
;     *(LAS u32x2*)(buf + OFF_KFT + kch * 32 + tq * 8) = (u32x2){(unsigned)kf[0] | ((unsigned)kf[1] << 16), (unsigned)kf[2] | ((unsigned)kf[3] << 16)};
;     if (tq == 0) *(LAS float*)(buf + OFF_D + kch * 4) = __builtin_amdgcn_exp2f(btot);
.Lhg_wd_a:
	s_barrier
	s_cmpk_gt_u32 s7, 0x7d
	s_cbranch_scc1 .LBB0_642
	s_add_i32 s41, s7, 5
	s_min_u32 s41, s41, 0x7f
	s_mul_i32 s41, s41, 0x1d400
	s_add_u32 s42, s38, s41
	s_addc_u32 s43, s39, 0
	s_add_i32 s41, s7, 1
	s_and_b32 s41, s41, 3
	s_mul_i32 s41, s41, 9792
	s_add_i32 m0, s41, s64
	s_nop 0
	global_load_lds_dwordx4 v138, s[42:43]
	s_cmp_lg_u32 s65, 7
	s_cbranch_scc1 .Lhg_nov_b
	s_add_i32 m0, s41, 0xf500
	s_nop 0
	global_load_lds_dwordx4 v139, s[42:43]
.Lhg_nov_b:
	s_add_i32 s41, s7, 2
	s_and_b32 s41, s41, 3
	s_mul_i32 s41, s41, 9792
	v_add_u32_e32 v140, s41, v136
	v_add_u32_e32 v141, s41, v137
	v_add_u32_e32 v153, 0x1080, v140
	ds_read2_b32 v[156:157], v153 offset1:64
	ds_read2_b32 v[158:159], v153 offset0:128 offset1:192
	ds_read2_b32 v[160:161], v140 offset1:64
	ds_read2_b32 v[162:163], v140 offset0:128 offset1:192
	ds_read2_b32 v[166:167], v141 offset1:16
	ds_read2_b32 v[168:169], v141 offset0:32 offset1:48
	s_waitcnt lgkmcnt(4)
	v_perm_b32 v0, v156, v156, v151
	v_perm_b32 v1, v157, v157, v151
	v_perm_b32 v3, v158, v158, v151
	v_perm_b32 v72, v159, v159, v151
	v_exp_f32_e32 v81, v0
	v_exp_f32_e32 v85, v1
	v_exp_f32_e32 v87, v3
	v_exp_f32_e32 v68, v72
	v_add_f32_e32 v1, v0, v1
	v_add_f32_e32 v3, v1, v3
	v_add_f32_e32 v75, v3, v72
	v_mov_b32_e32 v146, v75
	v_mov_b32_e32 v147, v75
	v_sub_f32_e32 v81, 1.0, v81
	v_sub_f32_e32 v85, 1.0, v85
	v_permlane16_swap_b32_e32 v146, v147
	v_sub_f32_e32 v87, 1.0, v87
	v_add_f32_e32 v148, v146, v147
	v_mov_b32_e32 v149, v148
	v_and_b32_e32 v150, v146, v145
	s_nop 0
	v_permlane32_swap_b32_e32 v148, v149
	v_cndmask_b32_e64 v72, 0, v148, s[48:49]
	v_add_f32_e32 v72, v72, v150
	s_waitcnt lgkmcnt(0)
	v_perm_b32 v66, v160, v160, v151
	v_perm_b32 v82, v161, v161, v151
	v_perm_b32 v74, v162, v162, v151
	v_perm_b32 v76, v163, v163, v151
	v_add_f32_e32 v0, v0, v72
	v_exp_f32_e32 v80, v0
	v_exp_f32_e64 v67, -v0
	v_add_f32_e32 v1, v1, v72
	v_exp_f32_e32 v84, v1
	v_exp_f32_e64 v83, -v1
	v_sub_f32_e32 v89, 1.0, v68
	v_add_f32_e32 v68, v75, v72
	v_add_f32_e32 v3, v3, v72
	v_pk_mul_f32 v[66:67], v[80:81], v[66:67]
	v_exp_f32_e32 v86, v3
	v_exp_f32_e64 v75, -v3
	v_exp_f32_e32 v88, v68
	v_exp_f32_e64 v77, -v68
	v_cvt_pk_bf16_f32 v170, v66, v67
	v_add_f32_e32 v0, v148, v149
	v_add_u32_e32 v184, v36, v43
	v_pk_mul_f32 v[66:67], v[84:85], v[82:83]
	v_and_b32_e32 v184, -4, v184
	v_cvt_pk_bf16_f32 v171, v66, v67
	v_pk_mul_f32 v[66:67], v[86:87], v[74:75]
	v_pk_mul_f32 v[74:75], v[88:89], v[76:77]
	v_add_u32_e32 v184, v184, v187
	v_cvt_pk_bf16_f32 v172, v66, v67
	v_cvt_pk_bf16_f32 v173, v74, v75
	v_perm_b32 v66, v171, v170, s17
	v_perm_b32 v67, v173, v172, s17
	v_cndmask_b32_e64 v174, v170, v172, s[44:45]
	v_cndmask_b32_e64 v175, v171, v173, s[44:45]
	v_cndmask_b32_e64 v176, v172, v170, s[44:45]
	v_cndmask_b32_e64 v177, v173, v171, s[44:45]
	v_add_u32_e32 v185, 0x1100, v184
	v_mov_b32_dpp v178, v174 quad_perm:[1,0,3,2] row_mask:0xf bank_mask:0xf
	v_mov_b32_dpp v179, v175 quad_perm:[1,0,3,2] row_mask:0xf bank_mask:0xf
	v_perm_b32 v180, v176, v178, v154
	v_perm_b32 v181, v177, v179, v154
	v_perm_b32 v182, v176, v178, v155
	v_perm_b32 v183, v177, v179, v155
	ds_write2_b32 v184, v180, v181 offset1:68
	ds_write2_b32 v185, v182, v183 offset1:68
	ds_write_b64 v38, v[66:67] offset:8704
	s_and_saveexec_b64 s[14:15], s[46:47]
	s_cbranch_execz .LBB0_638
	s_waitcnt lgkmcnt(9)
	v_exp_f32_e32 v0, v0
	v_add_u32_e32 v1, v27, v45
	ds_write_b32 v1, v0 offset:13824
